# static priority raise for waves 4-7 kept in retention phases only (attention phases run at equal priority)
# speedup vs baseline: 1.0085x; 1.0038x over previous
.LBB0_106:
	v_readfirstlane_b32 s0, v250
	s_cmpk_lt_u32 s0, 0x100
	s_cbranch_scc1 .LBB0_109
	s_bitcmp1_b32 s74, 0
	s_cbranch_scc0 .Lprio_skip
	s_setprio 1
.Lprio_skip:
	s_bitcmp0_b32 s74, 0
	s_mov_b64 s[0:1], -1
	s_cbranch_scc0 .LBB0_110
